# q-proj and pool GEMM (264 tiles each) spread one tile per CU over all XCDs when gridDim==512
# baseline (speedup 1.0000x reference)
; DEVI int xcd_first_tile() { return (blockIdx.x & 7) * (gridDim.x >> 3) + (blockIdx.x >> 3); }
; DEVI void run_phase(const Params& p, int ph, char* smem) {
;     ...
;     case 6: {
;       const u16* Bt = (const u16*)(p.ws + WS_WXQ) + (size_t)l * 256 * 1024;
;       for (int t = xcd_first_tile(); t < 132 * 2; t += xcd_tile_step()) {
;         int mt_, nt_; tile_coords(t, 132, 2, mt_, nt_);
;         gemm_tile<EPI_BF16>(p, xb, 1024, Bt, 1024, mt_ * 128, nt_ * 128, l, qx, 256, smem);
;       }
;     } break;
.LBB0_713:
	v_readlane_b32 s0, v254, 63
	s_and_b32 s38, 0xffff, s0
	s_cmp_lt_i32 s38, 4
	s_mov_b64 s[2:3], -1
	s_cbranch_scc1 .LBB0_838
	s_cmp_lt_i32 s38, 5
	s_cbranch_scc1 .LBB0_754
	s_cmp_gt_i32 s38, 5
	s_cbranch_scc0 .LBB0_744
	v_readlane_b32 s2, v250, 7
	s_cmpk_lg_u32 s2, 0x200
	s_cbranch_scc1 .Lq6_ochk
	v_readlane_b32 s2, v250, 0
	s_lshr_b32 s2, s2, 3
	s_cmp_lt_u32 s2, 33
	s_cbranch_scc0 .LBB0_743
	s_branch .Lq6_enter
.Lq6_ochk:
	v_readlane_b32 s2, v251, 23
	v_readlane_b32 s3, v251, 24
	s_andn2_b64 vcc, exec, s[2:3]
	s_cbranch_vccnz .LBB0_743
.Lq6_enter:
	v_readlane_b32 s0, v254, 62
	s_lshl_b32 s0, s0, 19
	v_readlane_b32 s2, v252, 35
	s_add_u32 s4, s2, s0
	v_readlane_b32 s2, v252, 36
	v_readlane_b32 s8, v250, 1
	s_addc_u32 s5, s2, 0
	v_readlane_b32 s12, v250, 5
	v_readlane_b32 s13, v250, 6
	s_add_u32 s6, s12, s0
	s_addc_u32 s7, s13, 0
	v_readlane_b32 s0, v254, 44
	v_readlane_b32 s9, v250, 2
	v_readlane_b32 s10, v250, 3
	v_readlane_b32 s11, v250, 4
	v_readlane_b32 s14, v250, 7
	v_readlane_b32 s15, v250, 8
	s_waitcnt vmcnt(0)
	v_readlane_b32 s2, v250, 7
	s_cmpk_lg_u32 s2, 0x200
	s_cbranch_scc1 .Lq6_keep
	v_readlane_b32 s2, v250, 0
	s_lshr_b32 s3, s2, 3
	s_and_b32 s2, s2, 7
	s_mul_i32 s2, s2, 33
	s_add_i32 s0, s2, s3
.Lq6_keep:
	s_branch .LBB0_719

; DEVI int xcd_first_tile() { return (blockIdx.x & 7) * (gridDim.x >> 3) + (blockIdx.x >> 3); }
; DEVI void run_phase(const Params& p, int ph, char* smem) {
;     ...
;       const u16* Bt = (const u16*)(p.ws + WS_POOLT) + (size_t)l * 65536;
;       for (int t = xcd_first_tile(); t < 132 * 2; t += xcd_tile_step()) {
;         int mt_, nt_; tile_coords(t, 132, 2, mt_, nt_);
;         gemm_tile<EPI_POOL>(p, (const u16*)(p.ws + WS_POOLED), 256, Bt, 256, mt_ * 128, nt_ * 128, l, nullptr, 0, smem);
;       }
.LBB0_874:
	v_writelane_b32 v252, s0, 54
	s_nop 1
	v_writelane_b32 v252, s1, 55
	s_or_b64 exec, exec, s[4:5]
	v_readlane_b32 s4, v250, 7
	s_cmpk_lg_u32 s4, 0x200
	s_cbranch_scc1 .Lp2_ochk
	v_readlane_b32 s4, v250, 0
	s_lshr_b32 s4, s4, 3
	s_cmp_lt_u32 s4, 33
	s_cbranch_scc0 .LBB0_881
	s_branch .Lp2_enter
.Lp2_ochk:
	v_readlane_b32 s4, v251, 23
	v_readlane_b32 s5, v251, 24
	s_andn2_b64 vcc, exec, s[4:5]
	s_cbranch_vccnz .LBB0_881
.Lp2_enter:
	s_lshl_b32 s0, s2, 17
	v_readlane_b32 s2, v251, 34
	v_readlane_b32 s3, v251, 35
	s_add_u32 s4, s2, s0
	v_readlane_b32 s0, v254, 62
	v_readlane_b32 s40, v250, 29
	s_addc_u32 s5, s3, 0
	s_lshl_b32 s0, s0, 10
	v_readlane_b32 s44, v250, 33
	v_readlane_b32 s45, v250, 34
	s_add_u32 s6, s44, s0
	s_addc_u32 s7, s45, 0
	v_readlane_b32 s0, v254, 44
	v_readlane_b32 s41, v250, 30
	v_readlane_b32 s42, v250, 31
	v_readlane_b32 s43, v250, 32
	v_readlane_b32 s46, v250, 35
	v_readlane_b32 s47, v250, 36
	v_readlane_b32 s48, v250, 37
	v_readlane_b32 s49, v250, 38
	v_readlane_b32 s50, v250, 39
	v_readlane_b32 s51, v250, 40
	v_readlane_b32 s52, v250, 41
	v_readlane_b32 s53, v250, 42
	v_readlane_b32 s54, v250, 43
	v_readlane_b32 s55, v250, 44
	v_readlane_b32 s2, v250, 7
	s_cmpk_lg_u32 s2, 0x200
	s_cbranch_scc1 .Lp2_keep
	v_readlane_b32 s2, v250, 0
	s_lshr_b32 s3, s2, 3
	s_and_b32 s2, s2, 7
	s_mul_i32 s2, s2, 33
	s_add_i32 s0, s2, s3
